# add O1 L1 full-line LDS-DMA relayout on top of v20
# speedup vs baseline: 1.0074x; 1.0043x over previous
; #define PG8_STAGE(bufoff, gbase, voff) do { _Pragma("unroll") for (int _i = 0; _i < 2; ++_i) \
;         __builtin_amdgcn_global_load_lds((const unsigned*)((const char*)(gbase) + (voff)[_i]), (LAS unsigned*)(lds + (bufoff) + ldsw + _i * 8192), 16, 0, 0); } while (0)
; #define PG8_WAIT_V(n) asm volatile("s_waitcnt vmcnt(" #n ")" ::: "memory")
; #define PG8_BAR __builtin_amdgcn_s_barrier()
; template <class Epi, class Sched>
; __device__ __forceinline__ void gemm_phase(LAS unsigned char* lds, const int K, const int lda, const int ldb, const Sched& S, const Epi& E) {
;     ...
;     for (int i = 0; i < 2; ++i) { int R, C; stage_rc(tid * 16 + i * 8192, R, C); const int Rb = (R & ~31) + perm32(R & 31);
;         voffA[i] = (unsigned)(R * lda + C) * 2u; voffB[i] = (unsigned)(Rb * ldb + C) * 2u; }
;     const size_t kstep = (size_t)(BK * 2);
;     const size_t hA = (size_t)HALF * lda * 2, hB = (size_t)HALF * ldb * 2;
;     const unsigned ldsw = (unsigned)wid * 1024u;
;     const int aoff = lds_byte(wr * 64 + fr, fq * 8), boff = lds_byte(wc * 32 + fr, fq * 8);
;     ...
;     const char* cA = S.aptr(cur); const char* cB = S.bptr(cur);
;     PG8_STAGE(PG8_SB(0, 0), cB, voffB); PG8_STAGE(PG8_SB(0, 1), cB + hB, voffB); PG8_STAGE(PG8_SA(0, 0), cA, voffA); PG8_STAGE(PG8_SA(0, 1), cA + hA, voffA);
;     if (wr == 1) PG8_BAR;
;     PG8_WAIT_V(2); PG8_BAR;
.LBB0_686:
	s_add_u32 s42, s30, 0x2e00000
	s_addc_u32 s43, s31, 0
	s_add_u32 s44, s30, 0x200000
	v_cndmask_b32_e64 v0, 0, 1, s[8:9]
	s_addc_u32 s45, s31, 0
	v_cmp_ne_u32_e64 s[4:5], 1, v0
	s_add_u32 s46, s30, 0xa00000
	s_addc_u32 s47, s31, 0
	v_writelane_b32 v255, s4, 26
	s_andn2_b64 vcc, exec, s[8:9]
	s_nop 0
	v_writelane_b32 v255, s5, 27
	s_cbranch_vccnz .LBB0_745
	v_ashrrev_i32_e32 v1, 31, v8
	v_lshrrev_b32_e32 v1, 26, v1
	v_add_u32_e32 v1, v8, v1
	v_ashrrev_i32_e32 v9, 6, v1
	v_bfe_i32 v1, v8, 27, 1
	v_lshlrev_b32_e32 v0, 4, v8
	v_lshrrev_b32_e32 v1, 22, v1
	v_add_u32_e32 v1, v0, v1
	v_and_b32_e32 v1, 0xfffffc00, v1
	v_sub_u32_e32 v1, v0, v1
	v_lshrrev_b32_e32 v2, 4, v1
	v_bitop3_b32 v1, v2, v1, 32 bitop3:0x6c
	v_ashrrev_i32_e32 v3, 31, v1
	v_lshrrev_b32_e32 v3, 26, v3
	v_add_u32_e32 v3, v1, v3
	v_lshlrev_b32_e32 v2, 3, v9
	v_ashrrev_i32_e32 v10, 6, v3
	v_and_b32_e32 v3, 0xc0, v3
	v_and_b32_e32 v2, -16, v2
	v_sub_u32_e32 v1, v1, v3
	v_mov_b32_e32 v3, 1
	v_add_u32_e32 v2, v10, v2
	v_ashrrev_i16_sdwa v1, v3, sext(v1) dst_sel:DWORD dst_unused:UNUSED_PAD src0_sel:DWORD src1_sel:BYTE_0
	v_lshlrev_b32_e32 v4, 5, v9
	v_bfe_i32 v11, v1, 0, 16
	v_lshlrev_b32_e32 v1, 1, v2
	v_lshrrev_b32_e32 v5, 2, v2
	v_and_b32_e32 v6, 3, v10
	s_mov_b32 s2, 0xfffe0
	v_and_b32_e32 v4, 32, v4
	v_and_b32_e32 v1, 24, v1
	v_and_b32_e32 v5, 4, v5
	v_and_or_b32 v6, v2, s2, v6
	v_or3_b32 v1, v6, v5, v1
	v_add_lshl_u32 v4, v4, v11, 1
	v_add_u32_e32 v0, 0x2000, v0
	v_and_b32_e32 v106, 63, v254
	v_lshrrev_b32_e32 v107, 6, v254
	v_lshrrev_b32_e32 v108, 3, v106
	v_lshl_add_u32 v109, v107, 3, v108
	v_and_b32_e32 v110, 1, v107
	v_bfe_u32 v111, v106, 4, 2
	v_lshl_add_u32 v111, v110, 2, v111
	v_and_b32_e32 v101, 7, v106
	v_xor_b32_e32 v111, v101, v111
	v_lshlrev_b32_e32 v111, 4, v111
	v_lshl_add_u32 v100, v109, 12, v111
	v_add_u32_e32 v101, 0x40000, v100
	v_lshrrev_b32_e32 v109, 5, v106
	v_lshlrev_b32_e32 v109, 3, v109
	v_lshl_add_u32 v109, v110, 4, v109
	v_bfe_u32 v110, v107, 1, 1
	v_lshl_add_u32 v109, v110, 2, v109
	v_and_b32_e32 v110, 3, v108
	v_add_u32_e32 v109, v109, v110
	v_lshrrev_b32_e32 v110, 2, v107
	v_lshl_add_u32 v109, v110, 5, v109
	v_lshl_add_u32 v102, v109, 12, v111
	v_add_u32_e32 v103, 0x40000, v102
	v_and_b32_e32 v106, 15, v254
	v_bfe_u32 v108, v254, 4, 2
	v_bfe_u32 v109, v254, 1, 3
	v_xor_b32_e32 v108, v108, v109
	v_lshlrev_b32_e32 v108, 4, v108
	v_lshl_add_u32 v108, v106, 7, v108
	v_lshrrev_b32_e32 v109, 8, v254
	v_lshl_add_u32 v104, v109, 13, v108
	v_and_b32_e32 v109, 3, v107
	v_lshl_add_u32 v105, v109, 12, v108
	v_mov_b32_e32 v130, v102
	v_ashrrev_i32_e32 v1, 31, v0
	v_lshrrev_b32_e32 v1, 22, v1
	v_add_u32_e32 v1, v0, v1
	v_ashrrev_i32_e32 v12, 10, v1
	v_mul_i32_i24_e32 v1, 0x400, v12
	v_sub_u32_e32 v0, v0, v1
	v_lshrrev_b32_e32 v1, 4, v0
	v_bitop3_b32 v0, v1, v0, 32 bitop3:0x6c
	v_mov_b32_e32 v128, v100
	v_ashrrev_i32_e32 v2, 31, v0
	v_lshrrev_b32_e32 v2, 26, v2
	v_add_u32_e32 v2, v0, v2
	v_lshlrev_b32_e32 v1, 3, v12
	v_ashrrev_i32_e32 v13, 6, v2
	v_and_b32_e32 v2, 0xc0, v2
	v_and_b32_e32 v1, -16, v1
	v_sub_u32_e32 v0, v0, v2
	s_ashr_i32 s1, s0, 6
	v_add_u32_e32 v1, v13, v1
	v_ashrrev_i16_sdwa v0, v3, sext(v0) dst_sel:DWORD dst_unused:UNUSED_PAD src0_sel:DWORD src1_sel:BYTE_0
	v_and_b32_e32 v3, 3, v13
	s_ashr_i32 s13, s12, 31
	s_ashr_i32 s67, s66, 31
	s_ashr_i32 s8, s0, 8
	v_and_or_b32 v3, v1, s2, v3
	s_lshl_b32 s2, s1, 10
	s_lshl_b64 s[6:7], s[12:13], 20
	s_lshl_b64 s[4:5], s[66:67], 20
	s_add_u32 s64, s46, s4
	v_lshlrev_b32_e32 v4, 5, v12
	v_bfe_i32 v14, v0, 0, 16
	v_lshlrev_b32_e32 v0, 1, v1
	v_lshrrev_b32_e32 v2, 2, v1
	s_addc_u32 s65, s47, s5
	s_add_i32 s4, s2, 0
	v_and_b32_e32 v4, 32, v4
	v_and_b32_e32 v0, 24, v0
	v_and_b32_e32 v2, 4, v2
	s_add_i32 m0, s4, 0x10000
	v_or3_b32 v0, v3, v2, v0
	v_add_lshl_u32 v2, v4, v14, 1
	global_load_lds_dwordx4 v130, s[64:65]
	s_add_i32 m0, s4, 0x12000
	v_mov_b32_e32 v134, v103
	s_add_u32 s10, s64, 0x80000
	global_load_lds_dwordx4 v134, s[64:65]
	s_addc_u32 s11, s65, 0
	s_add_i32 m0, s4, 0x14000
	v_mov_b32_e32 v132, v101
	global_load_lds_dwordx4 v130, s[10:11]
	s_add_i32 m0, s4, 0x16000
	s_add_u32 s68, s42, s6
	s_addc_u32 s69, s43, s7
	s_add_i32 s5, s4, 0x2000
	global_load_lds_dwordx4 v134, s[10:11]
	s_mov_b32 m0, s4
	s_add_u32 s10, s68, 0x80000
	global_load_lds_dwordx4 v128, s[68:69]
	s_mov_b32 m0, s5
	s_addc_u32 s11, s69, 0
	s_add_i32 s6, s4, 0x4000
	global_load_lds_dwordx4 v132, s[68:69]
	s_mov_b32 m0, s6
	s_add_i32 s7, s4, 0x6000
	global_load_lds_dwordx4 v128, s[10:11]
	s_mov_b32 m0, s7
	v_mov_b32_e32 v137, 0
	global_load_lds_dwordx4 v132, s[10:11]
	v_mov_b32_e32 v131, v137
	v_mov_b32_e32 v135, v137
	v_mov_b32_e32 v129, v137
	v_mov_b32_e32 v133, v137
	s_cmp_eq_u32 s8, 1
	s_mov_b32 s49, 0
	v_lshl_add_u64 v[6:7], s[64:65], 0, v[130:131]
	v_lshl_add_u64 v[4:5], s[64:65], 0, v[134:135]
	v_lshl_add_u64 v[0:1], s[68:69], 0, v[128:129]
	s_cselect_b64 s[50:51], -1, 0
	s_cmp_lg_u32 s8, 1
	v_lshl_add_u64 v[2:3], s[68:69], 0, v[132:133]
	s_cbranch_scc1 .LBB0_689
	s_barrier
; #define PG8_STAGE(bufoff, gbase, voff) do { _Pragma("unroll") for (int _i = 0; _i < 2; ++_i) \
;         __builtin_amdgcn_global_load_lds((const unsigned*)((const char*)(gbase) + (voff)[_i]), (LAS unsigned*)(lds + (bufoff) + ldsw + _i * 8192), 16, 0, 0); } while (0)
; #define PG8_WAIT_V(n) asm volatile("s_waitcnt vmcnt(" #n ")" ::: "memory")
; #define PG8_BAR __builtin_amdgcn_s_barrier()
; template <class Epi, class Sched>
; __device__ __forceinline__ void gemm_phase(LAS unsigned char* lds, const int K, const int lda, const int ldb, const Sched& S, const Epi& E) {
;     ...
;     const unsigned ldsw = (unsigned)wid * 1024u;
;     const int aoff = lds_byte(wr * 64 + fr, fq * 8), boff = lds_byte(wc * 32 + fr, fq * 8);
;     ...
;     PG8_STAGE(PG8_SB(1, 0), cB + kstep, voffB); PG8_STAGE(PG8_SA(1, 0), cA + kstep, voffA); PG8_STAGE(PG8_SB(1, 1), cB + hB + kstep, voffB);
;     PG8_WAIT_V(6); PG8_BAR;
.LBB0_689:
	v_and_b32_e32 v139, 15, v8
	v_and_b32_e32 v17, 48, v8
	v_lshlrev_b32_e32 v18, 2, v8
	s_mov_b64 s[52:53], 0x80
	s_and_b32 s10, s1, 3
	s_lshl_b32 s14, s8, 6
	s_lshl_b32 s8, s8, 13
	v_lshl_or_b32 v17, v139, 6, v17
	v_and_b32_e32 v18, 32, v18
	s_add_i32 m0, s4, 0x18000
	v_lshl_add_u64 v[6:7], v[6:7], 0, s[52:53]
	v_bitop3_b32 v19, v17, s8, v18 bitop3:0xde
	s_lshl_b32 s11, s10, 5
	s_lshl_b32 s8, s10, 12
	s_waitcnt vmcnt(2)
	s_barrier
	global_load_lds_dwordx4 v[6:7], off
	v_lshl_add_u64 v[4:5], v[4:5], 0, s[52:53]
	s_add_i32 m0, s4, 0x1a000
	s_add_i32 s15, s4, 0x8000
	s_add_i32 s17, s4, 0xa000
	v_mov_b32_e32 v143, v105
	global_load_lds_dwordx4 v[4:5], off
	v_lshl_add_u64 v[0:1], v[0:1], 0, s[52:53]
	s_mov_b32 m0, s15
	s_add_u32 s8, s64, 0x80080
	global_load_lds_dwordx4 v[0:1], off
	v_lshl_add_u64 v[0:1], v[2:3], 0, s[52:53]
	s_mov_b32 m0, s17
	s_addc_u32 s9, s65, 0
	global_load_lds_dwordx4 v[0:1], off
	s_add_i32 m0, s4, 0x1c000
	v_lshl_add_u64 v[0:1], s[8:9], 0, v[130:131]
	global_load_lds_dwordx4 v[0:1], off
	v_lshl_add_u64 v[0:1], s[8:9], 0, v[134:135]
	s_add_i32 m0, s4, 0x1e000
	s_cmpk_lt_u32 s0, 0x100
	global_load_lds_dwordx4 v[0:1], off
	s_cselect_b64 s[54:55], -1, 0
	s_lshl_b32 s0, s1, 12
	v_bfe_u32 v15, v8, 4, 2
	s_add_i32 s0, s0, 0
	v_bfe_u32 v2, v8, 3, 1
	v_bfe_u32 v7, v8, 3, 3
	v_lshlrev_b32_e32 v16, 3, v15
	s_add_i32 s0, s0, 0x20000
	v_lshlrev_b32_e32 v1, 10, v15
	v_xor_b32_e32 v3, v2, v15
	v_bitop3_b32 v4, v2, v15, 2 bitop3:0x36
	v_bitop3_b32 v5, v2, v15, 4 bitop3:0x36
	v_bitop3_b32 v2, v2, v15, 6 bitop3:0x36
	v_or_b32_e32 v15, 8, v7
	v_and_b32_e32 v141, 63, v8
	v_lshlrev_b32_e32 v0, 1, v8
	v_and_b32_e32 v6, 7, v8
	v_lshl_add_u32 v8, v7, 7, s0
	v_lshlrev_b32_e32 v138, 15, v7
	v_lshl_add_u32 v17, v15, 7, s0
	v_lshlrev_b32_e32 v140, 15, v15
	v_or_b32_e32 v15, 16, v7
	v_or_b32_e32 v7, 24, v7
	v_lshl_add_u32 v20, v15, 7, s0
	v_lshlrev_b32_e32 v142, 15, v15
	v_lshl_add_u32 v15, v7, 7, s0
	v_lshlrev_b32_e32 v144, 15, v7
	v_lshlrev_b32_e32 v7, 15, v12
	s_add_u32 s21, s30, 0x16e00000
	v_and_b32_e32 v7, 0xffff0000, v7
	s_addc_u32 s23, s31, 0
	v_lshl_add_u32 v7, v13, 12, v7
	v_and_b32_e32 v12, 1, v12
	s_add_u32 s24, s30, 0x12e00000
	v_and_b32_e32 v0, 14, v0
	v_lshl_or_b32 v7, v12, 6, v7
	s_addc_u32 s25, s31, 0
	s_lshl_b32 s1, s10, 20
	v_add_u32_e32 v0, s0, v0
	s_lshl_b32 s0, s10, 2
	v_mov_b32_e32 v146, v101
	v_lshlrev_b32_e32 v7, 15, v9
	s_add_u32 s0, s30, s0
	v_and_b32_e32 v7, 0xffff0000, v7
	s_addc_u32 s10, s31, 0
	v_lshl_add_u32 v7, v10, 12, v7
	v_and_b32_e32 v9, 1, v9
	s_waitcnt vmcnt(6)
	v_lshl_add_u32 v3, v3, 4, v0
	v_lshl_add_u32 v4, v4, 4, v0
	v_lshl_add_u32 v5, v5, 4, v0
	v_lshl_add_u32 v2, v2, 4, v0
	v_lshlrev_b32_e32 v0, 3, v6
	v_lshlrev_b32_e32 v6, 4, v6
	s_add_u32 s26, s0, 0x600000
	v_lshl_or_b32 v7, v9, 6, v7
	v_xor_b32_e32 v18, 16, v6
	v_xor_b32_e32 v21, 32, v6
	v_xor_b32_e32 v22, 48, v6
	s_addc_u32 s27, s10, 0
	v_mov_b32_e32 v148, v100
	s_add_i32 s79, 0, 0x10000
	s_add_i32 s80, 0, 0x14000
	v_mbcnt_lo_u32_b32 v7, -1, 0
	v_cmp_gt_u32_e64 s[8:9], 16, v141
	s_or_b32 s34, s1, 0x400000
	s_ashr_i32 s35, s3, 31
	s_ashr_i32 s78, s33, 31
	v_mov_b32_e32 v147, v137
	v_mov_b32_e32 v149, v137
	v_mov_b32_e32 v145, v104
	v_mbcnt_hi_u32_b32 v157, -1, v7
	s_mov_b32 s88, 0x800000
	v_lshlrev_b32_e32 v136, 1, v0
	s_lshl_b32 s48, s1, 1
	s_lshl_b32 s89, s11, 1
	v_lshlrev_b32_e32 v150, 1, v16
	v_mov_b64_e32 v[152:153], 0xe00
	v_mov_b64_e32 v[154:155], 0xdff
	v_add_u32_e32 v236, s79, v143
	v_add_u32_e32 v237, s80, v143
	v_xor_b32_e32 v247, 64, v145
	v_xor_b32_e32 v248, 64, v236
	v_xor_b32_e32 v249, 64, v237
	v_xor_b32_e32 v250, 64, v143
	v_mov_b32_e32 v156, 0x358637bd
	v_add_u32_e32 v238, v3, v1
	v_add_u32_e32 v239, v4, v1
	v_add_u32_e32 v240, v5, v1
	v_add_u32_e32 v241, v2, v1
	v_add_u32_e32 v242, v8, v6
	v_add_u32_e32 v243, v17, v18
	v_add_u32_e32 v244, v20, v21
	v_add_u32_e32 v245, v15, v22
	s_mov_b32 s90, s49
	s_barrier
	s_branch .LBB0_692

; #define PG8_STAGE(bufoff, gbase, voff) do { _Pragma("unroll") for (int _i = 0; _i < 2; ++_i) \
;         __builtin_amdgcn_global_load_lds((const unsigned*)((const char*)(gbase) + (voff)[_i]), (LAS unsigned*)(lds + (bufoff) + ldsw + _i * 8192), 16, 0, 0); } while (0)
; #define PG8_LDA(dst, b, h) do { _Pragma("unroll") for (int m = 0; m < 4; ++m) _Pragma("unroll") for (int k = 0; k < 2; ++k) dst[m][k] = *(const LAS bf16x8*)(lds + PG8_SA(b, h) + aoff + m * 2048 + k * 1024); } while (0)
; #define PG8_LDB(dst, b, h) do { _Pragma("unroll") for (int n = 0; n < 2; ++n) _Pragma("unroll") for (int k = 0; k < 2; ++k) dst[n][k] = *(const LAS bf16x8*)(lds + PG8_SB(b, h) + boff + n * 2048 + k * 1024); } while (0)
; #define PG8_MMA(ai, bj, At, Bt) do { __builtin_amdgcn_s_setprio(1); _Pragma("unroll") for (int m = 0; m < 4; ++m) _Pragma("unroll") for (int n = 0; n < 2; ++n) _Pragma("unroll") for (int k = 0; k < 2; ++k) \
;         acc[ai][bj][m][n] = __builtin_amdgcn_mfma_f32_16x16x32_bf16(Bt[n][k], At[m][k], acc[ai][bj][m][n], 0, 0, 0); __builtin_amdgcn_s_setprio(0); } while (0)
; #define PG8_WAIT_V(n) asm volatile("s_waitcnt vmcnt(" #n ")" ::: "memory")
; #define PG8_WAIT_L(n) asm volatile("s_waitcnt lgkmcnt(" #n ")" ::: "memory")
; #define PG8_BAR __builtin_amdgcn_s_barrier()
; #define PG8_SCHED __builtin_amdgcn_sched_barrier(0)
; template <class Epi, class Sched>
; __device__ __forceinline__ void gemm_phase(LAS unsigned char* lds, const int K, const int lda, const int ldb, const Sched& S, const Epi& E) {
;     ...
;             PG8_LDB(B0, 0, 0); PG8_LDB(B1, 0, 1); PG8_SCHED; PG8_LDA(At, 0, 0); PG8_STAGE(PG8_SA(1, 1), a1 + hA, voffA);
;             PG8_WAIT_V(8); PG8_WAIT_L(0); PG8_BAR; PG8_MMA(0, 0, At, B0); PG8_MMA(0, 1, At, B1); PG8_BAR; PG8_SCHED;
;             PG8_LDA(At, 0, 1); PG8_STAGE(PG8_SB(0, 0), b2, voffB); PG8_STAGE(PG8_SB(0, 1), b2 + hB, voffB); PG8_STAGE(PG8_SA(0, 0), a2, voffA);
.LBB0_695:
	s_waitcnt lgkmcnt(0)
	ds_read_b128 v[158:161], v236
	ds_read_b128 v[162:165], v248
	ds_read_b128 v[166:169], v236 offset:2048
	ds_read_b128 v[170:173], v248 offset:2048
	ds_read_b128 v[174:177], v237
	ds_read_b128 v[178:181], v249
	ds_read_b128 v[182:185], v237 offset:2048
	ds_read_b128 v[186:189], v249 offset:2048
	s_add_u32 s38, s64, 0xfff80080
	s_addc_u32 s39, s65, -1
	s_cmp_eq_u32 s29, 28
	s_cselect_b32 s71, s0, s39
	s_cselect_b32 s70, s1, s38
	s_cselect_b32 s69, s13, s28
	s_cselect_b32 s68, s18, s19
	v_lshl_add_u64 v[222:223], s[64:65], 0, v[148:149]
	s_add_i32 m0, s4, 0xc000
	ds_read_b128 v[190:193], v145
	ds_read_b128 v[194:197], v247
	ds_read_b128 v[198:201], v145 offset:2048
	ds_read_b128 v[202:205], v247 offset:2048
	ds_read_b128 v[206:209], v145 offset:4096
	ds_read_b128 v[210:213], v247 offset:4096
	ds_read_b128 v[214:217], v145 offset:6144
	ds_read_b128 v[218:221], v247 offset:6144
	global_load_lds_dwordx4 v[222:223], off
	v_lshl_add_u64 v[222:223], s[64:65], 0, v[146:147]
	s_add_i32 m0, s4, 0xe000
	s_nop 0
	global_load_lds_dwordx4 v[222:223], off
	s_waitcnt vmcnt(8)
	s_waitcnt lgkmcnt(0)
	s_barrier
	s_setprio 1
	s_waitcnt lgkmcnt(0)
	v_mfma_f32_16x16x32_bf16 v[124:127], v[158:161], v[190:193], v[124:127]
	v_mfma_f32_16x16x32_bf16 v[116:119], v[166:169], v[190:193], v[116:119]
	v_mfma_f32_16x16x32_bf16 v[108:111], v[158:161], v[198:201], v[108:111]
	v_mfma_f32_16x16x32_bf16 v[100:103], v[166:169], v[198:201], v[100:103]
	v_mfma_f32_16x16x32_bf16 v[92:95], v[158:161], v[206:209], v[92:95]
	v_mfma_f32_16x16x32_bf16 v[84:87], v[166:169], v[206:209], v[84:87]
	v_mfma_f32_16x16x32_bf16 v[76:79], v[158:161], v[214:217], v[76:79]
	v_mfma_f32_16x16x32_bf16 v[68:71], v[166:169], v[214:217], v[68:71]
	v_mfma_f32_16x16x32_bf16 v[124:127], v[162:165], v[194:197], v[124:127]
	v_mfma_f32_16x16x32_bf16 v[116:119], v[170:173], v[194:197], v[116:119]
	v_mfma_f32_16x16x32_bf16 v[108:111], v[162:165], v[202:205], v[108:111]
	v_mfma_f32_16x16x32_bf16 v[100:103], v[170:173], v[202:205], v[100:103]
	v_mfma_f32_16x16x32_bf16 v[92:95], v[162:165], v[210:213], v[92:95]
	v_mfma_f32_16x16x32_bf16 v[84:87], v[170:173], v[210:213], v[84:87]
	v_mfma_f32_16x16x32_bf16 v[76:79], v[162:165], v[218:221], v[76:79]
	v_mfma_f32_16x16x32_bf16 v[68:71], v[170:173], v[218:221], v[68:71]
	s_setprio 0
	s_setprio 1
	v_mfma_f32_16x16x32_bf16 v[120:123], v[174:177], v[190:193], v[120:123]
	v_mfma_f32_16x16x32_bf16 v[112:115], v[182:185], v[190:193], v[112:115]
	v_mfma_f32_16x16x32_bf16 v[104:107], v[174:177], v[198:201], v[104:107]
	v_mfma_f32_16x16x32_bf16 v[96:99], v[182:185], v[198:201], v[96:99]
	v_mfma_f32_16x16x32_bf16 v[88:91], v[174:177], v[206:209], v[88:91]
	v_mfma_f32_16x16x32_bf16 v[80:83], v[182:185], v[206:209], v[80:83]
	v_mfma_f32_16x16x32_bf16 v[72:75], v[174:177], v[214:217], v[72:75]
	v_mfma_f32_16x16x32_bf16 v[64:67], v[182:185], v[214:217], v[64:67]
	v_mfma_f32_16x16x32_bf16 v[120:123], v[178:181], v[194:197], v[120:123]
	v_mfma_f32_16x16x32_bf16 v[112:115], v[186:189], v[194:197], v[112:115]
	v_mfma_f32_16x16x32_bf16 v[104:107], v[178:181], v[202:205], v[104:107]
	v_mfma_f32_16x16x32_bf16 v[96:99], v[186:189], v[202:205], v[96:99]
	v_mfma_f32_16x16x32_bf16 v[88:91], v[178:181], v[210:213], v[88:91]
	v_mfma_f32_16x16x32_bf16 v[80:83], v[186:189], v[210:213], v[80:83]
	v_mfma_f32_16x16x32_bf16 v[72:75], v[178:181], v[218:221], v[72:75]
	v_mfma_f32_16x16x32_bf16 v[64:67], v[186:189], v[218:221], v[64:67]
	s_setprio 0
	s_barrier
	s_add_i32 s38, s79, s2
	v_lshl_add_u64 v[222:223], s[68:69], 0, v[130:131]
	s_mov_b32 m0, s38
	ds_read_b128 v[190:193], v145 offset:16384
	ds_read_b128 v[194:197], v247 offset:16384
	ds_read_b128 v[198:201], v145 offset:18432
	ds_read_b128 v[202:205], v247 offset:18432
	ds_read_b128 v[206:209], v145 offset:20480
	ds_read_b128 v[210:213], v247 offset:20480
	ds_read_b128 v[214:217], v145 offset:22528
	ds_read_b128 v[218:221], v247 offset:22528
	global_load_lds_dwordx4 v[222:223], off
	s_add_i32 m0, s38, 0x2000
	s_add_u32 s38, s68, 0x80000
	v_lshl_add_u64 v[224:225], s[68:69], 0, v[134:135]
	s_addc_u32 s39, s69, 0
	s_add_i32 s41, s80, s2
	global_load_lds_dwordx4 v[224:225], off
	v_lshl_add_u64 v[226:227], s[38:39], 0, v[130:131]
	s_mov_b32 m0, s41
	v_lshl_add_u64 v[228:229], s[70:71], 0, v[132:133]
	global_load_lds_dwordx4 v[226:227], off
	v_lshl_add_u64 v[226:227], s[38:39], 0, v[134:135]
	s_add_i32 m0, s41, 0x2000
	s_nop 0
	global_load_lds_dwordx4 v[226:227], off
	v_lshl_add_u64 v[226:227], s[70:71], 0, v[128:129]
	s_mov_b32 m0, s4
	s_nop 0
	global_load_lds_dwordx4 v[226:227], off
	s_mov_b32 m0, s5
	s_nop 0
	global_load_lds_dwordx4 v[228:229], off
	s_waitcnt vmcnt(8)
	s_waitcnt lgkmcnt(0)
	s_barrier
; #define PG8_STAGE(bufoff, gbase, voff) do { _Pragma("unroll") for (int _i = 0; _i < 2; ++_i) \
;         __builtin_amdgcn_global_load_lds((const unsigned*)((const char*)(gbase) + (voff)[_i]), (LAS unsigned*)(lds + (bufoff) + ldsw + _i * 8192), 16, 0, 0); } while (0)
; #define PG8_LDA(dst, b, h) do { _Pragma("unroll") for (int m = 0; m < 4; ++m) _Pragma("unroll") for (int k = 0; k < 2; ++k) dst[m][k] = *(const LAS bf16x8*)(lds + PG8_SA(b, h) + aoff + m * 2048 + k * 1024); } while (0)
; #define PG8_LDB(dst, b, h) do { _Pragma("unroll") for (int n = 0; n < 2; ++n) _Pragma("unroll") for (int k = 0; k < 2; ++k) dst[n][k] = *(const LAS bf16x8*)(lds + PG8_SB(b, h) + boff + n * 2048 + k * 1024); } while (0)
; #define PG8_MMA(ai, bj, At, Bt) do { __builtin_amdgcn_s_setprio(1); _Pragma("unroll") for (int m = 0; m < 4; ++m) _Pragma("unroll") for (int n = 0; n < 2; ++n) _Pragma("unroll") for (int k = 0; k < 2; ++k) \
;         acc[ai][bj][m][n] = __builtin_amdgcn_mfma_f32_16x16x32_bf16(Bt[n][k], At[m][k], acc[ai][bj][m][n], 0, 0, 0); __builtin_amdgcn_s_setprio(0); } while (0)
; #define PG8_WAIT_V(n) asm volatile("s_waitcnt vmcnt(" #n ")" ::: "memory")
; #define PG8_WAIT_L(n) asm volatile("s_waitcnt lgkmcnt(" #n ")" ::: "memory")
; #define PG8_BAR __builtin_amdgcn_s_barrier()
; #define PG8_SCHED __builtin_amdgcn_sched_barrier(0)
; template <class Epi, class Sched>
; __device__ __forceinline__ void gemm_phase(LAS unsigned char* lds, const int K, const int lda, const int ldb, const Sched& S, const Epi& E) {
;     ...
;             PG8_WAIT_V(8); PG8_WAIT_L(0); PG8_BAR; PG8_MMA(1, 0, At, B0); PG8_MMA(1, 1, At, B1); PG8_BAR; PG8_SCHED;
;             PG8_LDB(B0, 1, 0); PG8_LDB(B1, 1, 1); PG8_SCHED; PG8_LDA(At, 1, 0); PG8_STAGE(PG8_SA(0, 1), a2 + hA, voffA);
;             PG8_WAIT_V(8); PG8_WAIT_L(0); PG8_BAR; PG8_MMA(0, 0, At, B0); PG8_MMA(0, 1, At, B1); PG8_BAR; PG8_SCHED;
	s_setprio 1
	s_waitcnt lgkmcnt(0)
	v_mfma_f32_16x16x32_bf16 v[60:63], v[158:161], v[190:193], v[60:63]
	v_mfma_f32_16x16x32_bf16 v[52:55], v[166:169], v[190:193], v[52:55]
	v_mfma_f32_16x16x32_bf16 v[44:47], v[158:161], v[198:201], v[44:47]
	v_mfma_f32_16x16x32_bf16 v[36:39], v[166:169], v[198:201], v[36:39]
	v_mfma_f32_16x16x32_bf16 v[28:31], v[158:161], v[206:209], v[28:31]
	v_mfma_f32_16x16x32_bf16 v[20:23], v[166:169], v[206:209], v[20:23]
	v_mfma_f32_16x16x32_bf16 v[12:15], v[158:161], v[214:217], v[12:15]
	v_mfma_f32_16x16x32_bf16 v[4:7], v[166:169], v[214:217], v[4:7]
	v_mfma_f32_16x16x32_bf16 v[60:63], v[162:165], v[194:197], v[60:63]
	v_mfma_f32_16x16x32_bf16 v[52:55], v[170:173], v[194:197], v[52:55]
	v_mfma_f32_16x16x32_bf16 v[44:47], v[162:165], v[202:205], v[44:47]
	v_mfma_f32_16x16x32_bf16 v[36:39], v[170:173], v[202:205], v[36:39]
	v_mfma_f32_16x16x32_bf16 v[28:31], v[162:165], v[210:213], v[28:31]
	v_mfma_f32_16x16x32_bf16 v[20:23], v[170:173], v[210:213], v[20:23]
	v_mfma_f32_16x16x32_bf16 v[12:15], v[162:165], v[218:221], v[12:15]
	v_mfma_f32_16x16x32_bf16 v[4:7], v[170:173], v[218:221], v[4:7]
	s_setprio 0
	s_setprio 1
	v_mfma_f32_16x16x32_bf16 v[56:59], v[174:177], v[190:193], v[56:59]
	v_mfma_f32_16x16x32_bf16 v[48:51], v[182:185], v[190:193], v[48:51]
	v_mfma_f32_16x16x32_bf16 v[40:43], v[174:177], v[198:201], v[40:43]
	v_mfma_f32_16x16x32_bf16 v[32:35], v[182:185], v[198:201], v[32:35]
	v_mfma_f32_16x16x32_bf16 v[24:27], v[174:177], v[206:209], v[24:27]
	v_mfma_f32_16x16x32_bf16 v[16:19], v[182:185], v[206:209], v[16:19]
	v_mfma_f32_16x16x32_bf16 v[8:11], v[174:177], v[214:217], v[8:11]
	v_mfma_f32_16x16x32_bf16 v[0:3], v[182:185], v[214:217], v[0:3]
	v_mfma_f32_16x16x32_bf16 v[56:59], v[178:181], v[194:197], v[56:59]
	v_mfma_f32_16x16x32_bf16 v[48:51], v[186:189], v[194:197], v[48:51]
	v_mfma_f32_16x16x32_bf16 v[40:43], v[178:181], v[202:205], v[40:43]
	v_mfma_f32_16x16x32_bf16 v[32:35], v[186:189], v[202:205], v[32:35]
	v_mfma_f32_16x16x32_bf16 v[24:27], v[178:181], v[210:213], v[24:27]
	v_mfma_f32_16x16x32_bf16 v[16:19], v[186:189], v[210:213], v[16:19]
	v_mfma_f32_16x16x32_bf16 v[8:11], v[178:181], v[218:221], v[8:11]
	v_mfma_f32_16x16x32_bf16 v[0:3], v[186:189], v[218:221], v[0:3]
	s_setprio 0
	s_barrier
	s_add_i32 s41, 0, 0x18000
	v_add_u32_e32 v151, s41, v143
	v_add_u32_e32 v251, s41, v250
	s_add_i32 s57, 0, 0x1c000
	ds_read_b128 v[158:161], v151
	ds_read_b128 v[162:165], v251
	ds_read_b128 v[166:169], v151 offset:2048
	ds_read_b128 v[170:173], v251 offset:2048
	v_add_u32_e32 v151, s57, v143
	v_add_u32_e32 v251, s57, v250
	ds_read_b128 v[174:177], v151
	ds_read_b128 v[178:181], v251
	ds_read_b128 v[182:185], v151 offset:2048
	ds_read_b128 v[186:189], v251 offset:2048
	s_add_u32 s38, s70, 0x80000
	s_addc_u32 s39, s71, 0
	s_mov_b32 m0, s6
	v_lshl_add_u64 v[230:231], s[38:39], 0, v[128:129]
	ds_read_b128 v[190:193], v145 offset:32768
	ds_read_b128 v[194:197], v247 offset:32768
	ds_read_b128 v[198:201], v145 offset:34816
	ds_read_b128 v[202:205], v247 offset:34816
	ds_read_b128 v[206:209], v145 offset:36864
	ds_read_b128 v[210:213], v247 offset:36864
	ds_read_b128 v[214:217], v145 offset:38912
	ds_read_b128 v[218:221], v247 offset:38912
	global_load_lds_dwordx4 v[230:231], off
	v_lshl_add_u64 v[230:231], s[38:39], 0, v[132:133]
	s_mov_b32 m0, s7
	s_nop 0
	global_load_lds_dwordx4 v[230:231], off
	s_waitcnt vmcnt(8)
	s_waitcnt lgkmcnt(0)
	s_barrier
	s_setprio 1
	s_waitcnt lgkmcnt(0)
	v_mfma_f32_16x16x32_bf16 v[124:127], v[158:161], v[190:193], v[124:127]
	v_mfma_f32_16x16x32_bf16 v[116:119], v[166:169], v[190:193], v[116:119]
	v_mfma_f32_16x16x32_bf16 v[108:111], v[158:161], v[198:201], v[108:111]
	v_mfma_f32_16x16x32_bf16 v[100:103], v[166:169], v[198:201], v[100:103]
	v_mfma_f32_16x16x32_bf16 v[92:95], v[158:161], v[206:209], v[92:95]
	v_mfma_f32_16x16x32_bf16 v[84:87], v[166:169], v[206:209], v[84:87]
	v_mfma_f32_16x16x32_bf16 v[76:79], v[158:161], v[214:217], v[76:79]
	v_mfma_f32_16x16x32_bf16 v[68:71], v[166:169], v[214:217], v[68:71]
	v_mfma_f32_16x16x32_bf16 v[124:127], v[162:165], v[194:197], v[124:127]
	v_mfma_f32_16x16x32_bf16 v[116:119], v[170:173], v[194:197], v[116:119]
	v_mfma_f32_16x16x32_bf16 v[108:111], v[162:165], v[202:205], v[108:111]
	v_mfma_f32_16x16x32_bf16 v[100:103], v[170:173], v[202:205], v[100:103]
	v_mfma_f32_16x16x32_bf16 v[92:95], v[162:165], v[210:213], v[92:95]
	v_mfma_f32_16x16x32_bf16 v[84:87], v[170:173], v[210:213], v[84:87]
	v_mfma_f32_16x16x32_bf16 v[76:79], v[162:165], v[218:221], v[76:79]
	v_mfma_f32_16x16x32_bf16 v[68:71], v[170:173], v[218:221], v[68:71]
	s_setprio 0
	s_setprio 1
	v_mfma_f32_16x16x32_bf16 v[120:123], v[174:177], v[190:193], v[120:123]
	v_mfma_f32_16x16x32_bf16 v[112:115], v[182:185], v[190:193], v[112:115]
	v_mfma_f32_16x16x32_bf16 v[104:107], v[174:177], v[198:201], v[104:107]
	v_mfma_f32_16x16x32_bf16 v[96:99], v[182:185], v[198:201], v[96:99]
	v_mfma_f32_16x16x32_bf16 v[88:91], v[174:177], v[206:209], v[88:91]
	v_mfma_f32_16x16x32_bf16 v[80:83], v[182:185], v[206:209], v[80:83]
	v_mfma_f32_16x16x32_bf16 v[72:75], v[174:177], v[214:217], v[72:75]
	v_mfma_f32_16x16x32_bf16 v[64:67], v[182:185], v[214:217], v[64:67]
	v_mfma_f32_16x16x32_bf16 v[120:123], v[178:181], v[194:197], v[120:123]
	v_mfma_f32_16x16x32_bf16 v[112:115], v[186:189], v[194:197], v[112:115]
	v_mfma_f32_16x16x32_bf16 v[104:107], v[178:181], v[202:205], v[104:107]
	v_mfma_f32_16x16x32_bf16 v[96:99], v[186:189], v[202:205], v[96:99]
	v_mfma_f32_16x16x32_bf16 v[88:91], v[178:181], v[210:213], v[88:91]
	v_mfma_f32_16x16x32_bf16 v[80:83], v[186:189], v[210:213], v[80:83]
	v_mfma_f32_16x16x32_bf16 v[72:75], v[178:181], v[218:221], v[72:75]
	v_mfma_f32_16x16x32_bf16 v[64:67], v[186:189], v[218:221], v[64:67]
	s_setprio 0
	s_barrier
; #define PG8_STAGE(bufoff, gbase, voff) do { _Pragma("unroll") for (int _i = 0; _i < 2; ++_i) \
;         __builtin_amdgcn_global_load_lds((const unsigned*)((const char*)(gbase) + (voff)[_i]), (LAS unsigned*)(lds + (bufoff) + ldsw + _i * 8192), 16, 0, 0); } while (0)
; #define PG8_LDA(dst, b, h) do { _Pragma("unroll") for (int m = 0; m < 4; ++m) _Pragma("unroll") for (int k = 0; k < 2; ++k) dst[m][k] = *(const LAS bf16x8*)(lds + PG8_SA(b, h) + aoff + m * 2048 + k * 1024); } while (0)
; #define PG8_MMA(ai, bj, At, Bt) do { __builtin_amdgcn_s_setprio(1); _Pragma("unroll") for (int m = 0; m < 4; ++m) _Pragma("unroll") for (int n = 0; n < 2; ++n) _Pragma("unroll") for (int k = 0; k < 2; ++k) \
;         acc[ai][bj][m][n] = __builtin_amdgcn_mfma_f32_16x16x32_bf16(Bt[n][k], At[m][k], acc[ai][bj][m][n], 0, 0, 0); __builtin_amdgcn_s_setprio(0); } while (0)
; #define PG8_WAIT_V(n) asm volatile("s_waitcnt vmcnt(" #n ")" ::: "memory")
; #define PG8_WAIT_L(n) asm volatile("s_waitcnt lgkmcnt(" #n ")" ::: "memory")
; #define PG8_BAR __builtin_amdgcn_s_barrier()
; #define PG8_SCHED __builtin_amdgcn_sched_barrier(0)
; template <class Epi, class Sched>
; __device__ __forceinline__ void gemm_phase(LAS unsigned char* lds, const int K, const int lda, const int ldb, const Sched& S, const Epi& E) {
;     ...
;             PG8_LDA(At, 1, 1); PG8_STAGE(PG8_SB(1, 0), b3, voffB); PG8_STAGE(PG8_SB(1, 1), b3 + hB, voffB); PG8_STAGE(PG8_SA(1, 0), a3, voffA);
;             PG8_WAIT_V(8); PG8_WAIT_L(0); PG8_BAR; PG8_MMA(1, 0, At, B0); PG8_MMA(1, 1, At, B1); PG8_BAR; PG8_SCHED;
;         }
	s_add_i32 s38, s41, s2
	v_lshl_add_u64 v[222:223], v[222:223], 0, s[52:53]
	s_mov_b32 m0, s38
	ds_read_b128 v[190:193], v145 offset:49152
	ds_read_b128 v[194:197], v247 offset:49152
	ds_read_b128 v[198:201], v145 offset:51200
	ds_read_b128 v[202:205], v247 offset:51200
	ds_read_b128 v[206:209], v145 offset:53248
	ds_read_b128 v[210:213], v247 offset:53248
	ds_read_b128 v[214:217], v145 offset:55296
	ds_read_b128 v[218:221], v247 offset:55296
	global_load_lds_dwordx4 v[222:223], off
	s_add_i32 m0, s38, 0x2000
	s_add_u32 s38, s68, 0x80080
	v_lshl_add_u64 v[222:223], v[224:225], 0, s[52:53]
	s_addc_u32 s39, s69, 0
	s_add_i32 s41, s57, s2
	global_load_lds_dwordx4 v[222:223], off
	v_lshl_add_u64 v[222:223], s[38:39], 0, v[130:131]
	s_mov_b32 m0, s41
	s_nop 0
	global_load_lds_dwordx4 v[222:223], off
	v_lshl_add_u64 v[222:223], s[38:39], 0, v[134:135]
	s_add_i32 m0, s41, 0x2000
	s_nop 0
	global_load_lds_dwordx4 v[222:223], off
	v_lshl_add_u64 v[222:223], v[226:227], 0, s[52:53]
	s_mov_b32 m0, s15
	s_nop 0
	global_load_lds_dwordx4 v[222:223], off
	v_lshl_add_u64 v[222:223], v[228:229], 0, s[52:53]
	s_mov_b32 m0, s17
	s_nop 0
	global_load_lds_dwordx4 v[222:223], off
	s_waitcnt vmcnt(8)
	s_waitcnt lgkmcnt(0)
	s_barrier
	s_setprio 1
	s_waitcnt lgkmcnt(0)
	v_mfma_f32_16x16x32_bf16 v[60:63], v[158:161], v[190:193], v[60:63]
	v_mfma_f32_16x16x32_bf16 v[52:55], v[166:169], v[190:193], v[52:55]
	v_mfma_f32_16x16x32_bf16 v[44:47], v[158:161], v[198:201], v[44:47]
	v_mfma_f32_16x16x32_bf16 v[36:39], v[166:169], v[198:201], v[36:39]
	v_mfma_f32_16x16x32_bf16 v[28:31], v[158:161], v[206:209], v[28:31]
	v_mfma_f32_16x16x32_bf16 v[20:23], v[166:169], v[206:209], v[20:23]
	v_mfma_f32_16x16x32_bf16 v[12:15], v[158:161], v[214:217], v[12:15]
	v_mfma_f32_16x16x32_bf16 v[4:7], v[166:169], v[214:217], v[4:7]
	v_mfma_f32_16x16x32_bf16 v[60:63], v[162:165], v[194:197], v[60:63]
	v_mfma_f32_16x16x32_bf16 v[52:55], v[170:173], v[194:197], v[52:55]
	v_mfma_f32_16x16x32_bf16 v[44:47], v[162:165], v[202:205], v[44:47]
	v_mfma_f32_16x16x32_bf16 v[36:39], v[170:173], v[202:205], v[36:39]
	v_mfma_f32_16x16x32_bf16 v[28:31], v[162:165], v[210:213], v[28:31]
	v_mfma_f32_16x16x32_bf16 v[20:23], v[170:173], v[210:213], v[20:23]
	v_mfma_f32_16x16x32_bf16 v[12:15], v[162:165], v[218:221], v[12:15]
	v_mfma_f32_16x16x32_bf16 v[4:7], v[170:173], v[218:221], v[4:7]
	s_setprio 0
	s_setprio 1
	v_mfma_f32_16x16x32_bf16 v[56:59], v[174:177], v[190:193], v[56:59]
	v_mfma_f32_16x16x32_bf16 v[48:51], v[182:185], v[190:193], v[48:51]
	v_mfma_f32_16x16x32_bf16 v[40:43], v[174:177], v[198:201], v[40:43]
	v_mfma_f32_16x16x32_bf16 v[32:35], v[182:185], v[198:201], v[32:35]
	v_mfma_f32_16x16x32_bf16 v[24:27], v[174:177], v[206:209], v[24:27]
	v_mfma_f32_16x16x32_bf16 v[16:19], v[182:185], v[206:209], v[16:19]
	v_mfma_f32_16x16x32_bf16 v[8:11], v[174:177], v[214:217], v[8:11]
	v_mfma_f32_16x16x32_bf16 v[0:3], v[182:185], v[214:217], v[0:3]
	v_mfma_f32_16x16x32_bf16 v[56:59], v[178:181], v[194:197], v[56:59]
	v_mfma_f32_16x16x32_bf16 v[48:51], v[186:189], v[194:197], v[48:51]
	v_mfma_f32_16x16x32_bf16 v[40:43], v[178:181], v[202:205], v[40:43]
	v_mfma_f32_16x16x32_bf16 v[32:35], v[186:189], v[202:205], v[32:35]
	v_mfma_f32_16x16x32_bf16 v[24:27], v[178:181], v[210:213], v[24:27]
	v_mfma_f32_16x16x32_bf16 v[16:19], v[186:189], v[210:213], v[16:19]
	v_mfma_f32_16x16x32_bf16 v[8:11], v[178:181], v[218:221], v[8:11]
	v_mfma_f32_16x16x32_bf16 v[0:3], v[186:189], v[218:221], v[0:3]
	s_setprio 0
	s_barrier
	s_add_i32 s29, s29, 2
	s_add_u32 s19, s19, 0x100
	s_addc_u32 s28, s28, 0
	s_add_u32 s64, s64, 0x100
	s_addc_u32 s65, s65, 0
	s_cmp_gt_u32 s29, 29
	s_cbranch_scc0 .LBB0_695
	s_and_b64 vcc, exec, s[54:55]
	s_cbranch_vccz .LBB0_698
	s_barrier
